# pool unit set-up: the four first-tile g_pool loads stay in flight together (three serialized vmcnt(0) waits removed per variant)
# speedup vs baseline: 1.0003x; 1.0003x over previous
.LBB0_123:
	s_or_b64 exec, exec, s[18:19]
	s_lshl_b64 s[6:7], s[0:1], 10
	s_lshl_b32 s10, s20, 1
	s_and_b32 s10, s10, 0x3fffff8
	s_lshl_b64 s[6:7], s[6:7], 1
	v_readlane_b32 s18, v253, 42
	v_readlane_b32 s19, v253, 43
	s_add_u32 s6, s18, s6
	v_ashrrev_i32_e32 v107, 31, v106
	v_and_b32_e32 v148, 15, v110
	s_addc_u32 s7, s19, s7
	v_lshlrev_b64 v[106:107], 1, v[106:107]
	v_or_b32_e32 v103, s2, v148
	v_lshl_add_u64 v[108:109], s[6:7], 0, v[106:107]
	v_lshlrev_b32_e32 v112, 1, v111
	v_mov_b32_e32 v113, v1
	s_movk_i32 s2, 0x210
	v_lshl_add_u64 v[108:109], v[108:109], 0, v[112:113]
	v_lshlrev_b32_e32 v114, 11, v103
	v_mov_b32_e32 v115, v1
	v_lshlrev_b32_e32 v103, 4, v110
	v_mul_lo_u32 v105, v144, s2
	v_lshl_add_u64 v[108:109], v[108:109], 0, v[114:115]
	v_mul_lo_u32 v111, v145, s2
	v_mul_lo_u32 v114, v146, s2
	v_mul_lo_u32 v115, v147, s2
	v_and_b32_e32 v103, 0x1f0, v103
	v_add_u32_e32 v105, 0, v105
	v_add_u32_e32 v111, 0, v111
	v_add_u32_e32 v114, 0, v114
	v_add_u32_e32 v115, 0, v115
	v_add_u32_e32 v149, v105, v103
	global_load_dwordx4 v[130:133], v[108:109], off offset:1536
	v_add_u32_e32 v150, v111, v103
	v_add_u32_e32 v151, v114, v103
	v_add_u32_e32 v152, v115, v103
	v_add_u32_e32 v153, v105, v104
	s_waitcnt vmcnt(4)
	ds_write_b128 v149, v[82:85] offset:8448
	s_waitcnt vmcnt(3)
	ds_write_b128 v150, v[86:89] offset:8448
	s_waitcnt vmcnt(2)
	ds_write_b128 v151, v[90:93] offset:8448
	s_waitcnt vmcnt(1)
	ds_write_b128 v152, v[94:97] offset:8448
	ds_write_b128 v153, v[98:101]
	v_add_co_u32_e32 v82, vcc, s97, v108
	s_movk_i32 s2, 0x840
	v_addc_co_u32_e32 v83, vcc, 0, v109, vcc
	global_load_dwordx4 v[126:129], v[82:83], off offset:1536
	v_add_co_u32_e32 v82, vcc, s4, v108
	v_readlane_b32 s6, v253, 40
	v_addc_co_u32_e32 v83, vcc, 0, v109, vcc
	global_load_dwordx4 v[122:125], v[82:83], off offset:1536
	v_add_co_u32_e32 v82, vcc, s96, v108
	v_readlane_b32 s7, v253, 41
	v_addc_co_u32_e32 v83, vcc, 0, v109, vcc
	global_load_dwordx4 v[98:101], v[82:83], off offset:1536
	v_add_u32_e32 v82, 0, v104
	v_mul_lo_u32 v83, v144, s2
	v_add_u32_e32 v85, 0, v83
	v_add_u32_e32 v154, v82, v83
	v_lshl_add_u64 v[82:83], s[18:19], 0, v[106:107]
	s_lshl_b64 s[0:1], s[0:1], 12
	v_lshl_add_u64 v[138:139], s[6:7], 0, v[0:1]
	v_mul_u32_u24_e32 v0, 0x210, v148
	v_lshlrev_b32_e32 v86, 12, v148
	v_lshl_add_u64 v[140:141], v[82:83], 0, v[112:113]
	s_bfe_u32 s2, s20, 0x30002
	v_and_or_b32 v82, v110, 48, s0
	v_mov_b32_e32 v83, s1
	v_add3_u32 v155, 0, v102, v0
	v_lshl_or_b32 v0, s2, 21, v86
	v_lshl_add_u64 v[82:83], v[82:83], 0, v[106:107]
	v_lshlrev_b32_e32 v84, 2, v144
	v_lshl_add_u64 v[82:83], v[82:83], 0, v[0:1]
	s_mov_b32 s11, 1
	s_mov_b64 s[42:43], 0
	v_add_u32_e32 v156, 0xa500, v155
	v_lshl_add_u32 v157, s2, 9, v84
	v_lshl_add_u64 v[142:143], s[90:91], 0, v[82:83]
	v_add_u32_e32 v158, v85, v104
	s_waitcnt vmcnt(0)

.LBB0_129:
	s_or_b64 exec, exec, s[18:19]
	s_lshl_b64 s[6:7], s[0:1], 10
	s_lshl_b32 s10, s20, 1
	s_and_b32 s10, s10, 0x3fffff8
	s_lshl_b64 s[6:7], s[6:7], 1
	v_readlane_b32 s18, v253, 42
	v_readlane_b32 s19, v253, 43
	s_add_u32 s6, s18, s6
	v_ashrrev_i32_e32 v107, 31, v106
	v_and_b32_e32 v148, 15, v110
	s_addc_u32 s7, s19, s7
	v_lshlrev_b64 v[106:107], 1, v[106:107]
	v_or_b32_e32 v103, s2, v148
	v_lshl_add_u64 v[108:109], s[6:7], 0, v[106:107]
	v_lshlrev_b32_e32 v112, 1, v111
	v_mov_b32_e32 v113, v1
	s_movk_i32 s2, 0x210
	v_lshl_add_u64 v[108:109], v[108:109], 0, v[112:113]
	v_lshlrev_b32_e32 v114, 11, v103
	v_mov_b32_e32 v115, v1
	v_lshlrev_b32_e32 v103, 4, v110
	v_mul_lo_u32 v105, v144, s2
	v_lshl_add_u64 v[108:109], v[108:109], 0, v[114:115]
	v_mul_lo_u32 v111, v145, s2
	v_mul_lo_u32 v114, v146, s2
	v_mul_lo_u32 v115, v147, s2
	v_and_b32_e32 v103, 0x1f0, v103
	v_add_u32_e32 v105, 0, v105
	v_add_u32_e32 v111, 0, v111
	v_add_u32_e32 v114, 0, v114
	v_add_u32_e32 v115, 0, v115
	v_add_u32_e32 v149, v105, v103
	global_load_dwordx4 v[130:133], v[108:109], off offset:1024
	v_add_u32_e32 v150, v111, v103
	v_add_u32_e32 v151, v114, v103
	v_add_u32_e32 v152, v115, v103
	v_add_u32_e32 v153, v105, v104
	s_waitcnt vmcnt(4)
	ds_write_b128 v149, v[82:85] offset:8448
	s_waitcnt vmcnt(3)
	ds_write_b128 v150, v[86:89] offset:8448
	s_waitcnt vmcnt(2)
	ds_write_b128 v151, v[90:93] offset:8448
	s_waitcnt vmcnt(1)
	ds_write_b128 v152, v[94:97] offset:8448
	ds_write_b128 v153, v[98:101]
	v_add_co_u32_e32 v82, vcc, s97, v108
	s_movk_i32 s2, 0x840
	v_addc_co_u32_e32 v83, vcc, 0, v109, vcc
	global_load_dwordx4 v[126:129], v[82:83], off offset:1024
	v_add_co_u32_e32 v82, vcc, s4, v108
	v_readlane_b32 s6, v253, 40
	v_addc_co_u32_e32 v83, vcc, 0, v109, vcc
	global_load_dwordx4 v[122:125], v[82:83], off offset:1024
	v_add_co_u32_e32 v82, vcc, s96, v108
	v_readlane_b32 s7, v253, 41
	v_addc_co_u32_e32 v83, vcc, 0, v109, vcc
	global_load_dwordx4 v[98:101], v[82:83], off offset:1024
	v_add_u32_e32 v82, 0, v104
	v_mul_lo_u32 v83, v144, s2
	v_add_u32_e32 v85, 0, v83
	v_add_u32_e32 v154, v82, v83
	v_lshl_add_u64 v[82:83], s[18:19], 0, v[106:107]
	s_lshl_b64 s[0:1], s[0:1], 12
	v_lshl_add_u64 v[138:139], s[6:7], 0, v[0:1]
	v_mul_u32_u24_e32 v0, 0x210, v148
	v_lshlrev_b32_e32 v86, 12, v148
	v_lshl_add_u64 v[140:141], v[82:83], 0, v[112:113]
	s_bfe_u32 s2, s20, 0x30002
	v_and_or_b32 v82, v110, 48, s0
	v_mov_b32_e32 v83, s1
	v_add3_u32 v155, 0, v102, v0
	v_lshl_or_b32 v0, s2, 21, v86
	v_lshl_add_u64 v[82:83], v[82:83], 0, v[106:107]
	v_lshlrev_b32_e32 v84, 2, v144
	v_lshl_add_u64 v[82:83], v[82:83], 0, v[0:1]
	s_mov_b32 s11, 1
	s_mov_b64 s[42:43], 0
	v_add_u32_e32 v156, 0xa500, v155
	v_lshl_add_u32 v157, s2, 9, v84
	v_lshl_add_u64 v[142:143], s[90:91], 0, v[82:83]
	v_add_u32_e32 v158, v85, v104
	s_waitcnt vmcnt(0)

.LBB0_137:
	s_or_b64 exec, exec, s[18:19]
	s_movk_i32 s2, 0x210
	v_lshlrev_b32_e32 v103, 4, v106
	v_mul_lo_u32 v104, v172, s2
	v_and_b32_e32 v103, 0x1f0, v103
	v_add_u32_e32 v104, 0, v104
	v_add_u32_e32 v164, v104, v103
	s_waitcnt vmcnt(3)
	ds_write_b128 v164, v[86:89] offset:8448
	v_mul_lo_u32 v86, v174, s2
	v_add_u32_e32 v86, 0, v86
	v_add_u32_e32 v165, v86, v103
	s_waitcnt vmcnt(2)
	ds_write_b128 v165, v[82:85] offset:8448
	v_mul_lo_u32 v82, v175, s2
	v_add_u32_e32 v82, 0, v82
	v_and_b32_e32 v171, 15, v106
	v_add_u32_e32 v166, v82, v103
	s_waitcnt vmcnt(1)
	ds_write_b128 v166, v[94:97] offset:8448
	s_lshl_b64 s[0:1], s[0:1], 1
	v_readlane_b32 s6, v253, 42
	v_ashrrev_i32_e32 v139, 31, v138
	v_mul_u32_u24_e32 v96, 0x210, v171
	v_mul_lo_u32 v82, v173, s2
	v_readlane_b32 s7, v253, 43
	s_add_u32 s0, s6, s0
	v_lshlrev_b64 v[94:95], 1, v[138:139]
	s_movk_i32 s2, 0x840
	v_add3_u32 v170, 0, v0, v96
	v_and_b32_e32 v96, 48, v106
	v_mov_b32_e32 v97, v1
	v_add_u32_e32 v168, v104, v102
	s_addc_u32 s1, s7, s1
	v_mul_lo_u32 v108, v172, s2
	s_lshr_b32 s2, s20, 2
	v_lshl_add_u64 v[104:105], v[96:97], 0, v[94:95]
	s_mov_b64 s[6:7], 0x1a000000
	s_lshl_b32 s2, s2, 9
	v_lshl_add_u64 v[144:145], v[104:105], 0, s[6:7]
	s_mov_b64 s[6:7], 0x1a008000
	s_or_b32 s11, s2, 64
	s_bfe_u32 s2, s20, 0x30002
	v_lshl_add_u64 v[148:149], v[104:105], 0, s[6:7]
	s_mov_b64 s[6:7], 0x1a010000
	s_lshl_b32 s18, s2, 9
	v_lshl_add_u64 v[150:151], v[104:105], 0, s[6:7]
	s_mov_b64 s[6:7], 0x1a018000
	v_lshl_add_u64 v[152:153], v[104:105], 0, s[6:7]
	v_add_u32_e32 v104, s18, v173
	v_ashrrev_i32_e32 v105, 31, v104
	v_lshlrev_b64 v[104:105], 11, v[104:105]
	v_or_b32_e32 v104, v104, v103
	s_mov_b64 s[6:7], 0x16020000
	v_lshl_add_u64 v[154:155], v[104:105], 0, s[6:7]
	v_add_u32_e32 v104, s18, v175
	v_ashrrev_i32_e32 v105, 31, v104
	v_add_u32_e32 v82, 0, v82
	v_lshlrev_b64 v[104:105], 11, v[104:105]
	v_add_u32_e32 v167, v82, v103
	v_or_b32_e32 v84, s15, v171
	v_lshl_add_u64 v[82:83], s[0:1], 0, v[94:95]
	v_lshlrev_b32_e32 v142, 1, v107
	v_mov_b32_e32 v143, v1
	v_or_b32_e32 v104, v104, v103
	v_lshl_add_u64 v[82:83], v[82:83], 0, v[142:143]
	v_lshlrev_b32_e32 v84, 11, v84
	v_mov_b32_e32 v85, v1
	v_lshl_add_u64 v[156:157], v[104:105], 0, s[6:7]
	v_add_u32_e32 v104, s18, v174
	v_lshl_add_u64 v[82:83], v[82:83], 0, v[84:85]
	v_ashrrev_i32_e32 v105, 31, v104
	v_add_co_u32_e32 v84, vcc, s97, v82
	v_lshlrev_b64 v[104:105], 11, v[104:105]
	s_waitcnt vmcnt(0)
	ds_write_b128 v167, v[90:93] offset:8448
	ds_write_b128 v168, v[98:101]
	global_load_dwordx4 v[98:101], v[82:83], off
	v_addc_co_u32_e32 v85, vcc, 0, v83, vcc
	v_or_b32_e32 v104, v104, v103
	global_load_dwordx4 v[90:93], v[84:85], off
	v_add_co_u32_e32 v84, vcc, s4, v82
	v_or_b32_e32 v0, s18, v171
	v_lshl_add_u64 v[158:159], v[104:105], 0, s[6:7]
	v_add_u32_e32 v104, s18, v172
	v_addc_co_u32_e32 v85, vcc, 0, v83, vcc
	s_lshl_b64 s[0:1], s[42:43], 12
	v_lshl_or_b32 v0, v0, 11, v197
	v_ashrrev_i32_e32 v105, 31, v104
	v_add_co_u32_e32 v82, vcc, s96, v82
	v_lshl_add_u64 v[146:147], s[90:91], 0, v[0:1]
	v_lshlrev_b64 v[104:105], 11, v[104:105]
	v_or_b32_e32 v96, s0, v96
	v_mov_b32_e32 v97, s1
	v_lshlrev_b32_e32 v0, 12, v171
	global_load_dwordx4 v[86:89], v[84:85], off
	v_addc_co_u32_e32 v83, vcc, 0, v83, vcc
	v_add_u32_e32 v107, 0, v102
	v_add_u32_e32 v109, 0, v108
	v_or_b32_e32 v104, v104, v103
	v_lshl_add_u64 v[94:95], v[96:97], 0, v[94:95]
	v_lshl_or_b32 v0, s2, 21, v0
	s_mov_b32 s10, 0
	global_load_dwordx4 v[82:85], v[82:83], off
	v_add_u32_e32 v169, 0xa500, v170
	v_lshl_add_u64 v[160:161], v[104:105], 0, s[6:7]
	v_lshl_add_u64 v[162:163], v[94:95], 0, v[0:1]
	v_lshl_add_u32 v141, v172, 2, s18
	s_mov_b64 s[44:45], 0
	v_add_u32_e32 v0, v107, v108
	v_add_u32_e32 v176, v109, v102
	s_waitcnt vmcnt(0)

.LBB0_143:
	s_or_b64 exec, exec, s[18:19]
	s_movk_i32 s2, 0x210
	v_lshlrev_b32_e32 v103, 4, v106
	v_mul_lo_u32 v104, v172, s2
	v_and_b32_e32 v103, 0x1f0, v103
	v_add_u32_e32 v104, 0, v104
	v_add_u32_e32 v164, v104, v103
	s_waitcnt vmcnt(3)
	ds_write_b128 v164, v[86:89] offset:8448
	v_mul_lo_u32 v86, v175, s2
	v_add_u32_e32 v86, 0, v86
	v_add_u32_e32 v165, v86, v103
	s_waitcnt vmcnt(2)
	ds_write_b128 v165, v[82:85] offset:8448
	v_mul_lo_u32 v82, v176, s2
	v_add_u32_e32 v82, 0, v82
	s_lshl_b64 s[0:1], s[0:1], 1
	v_readlane_b32 s6, v253, 42
	v_add_u32_e32 v166, v82, v103
	v_mul_lo_u32 v82, v174, s2
	v_readlane_b32 s7, v253, 43
	s_add_u32 s0, s6, s0
	v_ashrrev_i32_e32 v139, 31, v138
	s_waitcnt vmcnt(1)
	ds_write_b128 v166, v[94:97] offset:8448
	v_add_u32_e32 v82, 0, v82
	s_addc_u32 s1, s7, s1
	v_lshlrev_b64 v[94:95], 1, v[138:139]
	v_and_b32_e32 v171, 15, v106
	v_add_u32_e32 v167, v82, v103
	v_lshl_add_u64 v[82:83], s[0:1], 0, v[94:95]
	s_movk_i32 s0, 0x840
	v_mul_lo_u32 v108, v172, s0
	v_mul_u32_u24_e32 v96, 0x210, v171
	s_lshr_b32 s0, s20, 2
	v_add3_u32 v170, 0, v0, v96
	s_lshl_b32 s0, s0, 9
	v_and_b32_e32 v96, 48, v106
	v_mov_b32_e32 v97, v1
	v_add_u32_e32 v168, v104, v102
	s_or_b32 s11, s0, 64
	v_lshl_add_u64 v[104:105], v[96:97], 0, v[94:95]
	s_mov_b64 s[0:1], 0x1a018200
	v_lshl_add_u64 v[144:145], v[104:105], 0, s[0:1]
	s_mov_b64 s[0:1], 0x1a010200
	s_bfe_u32 s2, s20, 0x30002
	v_lshl_add_u64 v[148:149], v[104:105], 0, s[0:1]
	s_mov_b64 s[0:1], 0x1a008200
	s_lshl_b32 s6, s2, 9
	v_lshl_add_u64 v[150:151], v[104:105], 0, s[0:1]
	s_mov_b64 s[0:1], 0x1a000200
	v_lshl_add_u64 v[152:153], v[104:105], 0, s[0:1]
	v_add_u32_e32 v104, s6, v174
	v_ashrrev_i32_e32 v105, 31, v104
	v_lshlrev_b64 v[104:105], 11, v[104:105]
	v_or_b32_e32 v104, v104, v103
	s_mov_b64 s[0:1], 0x16020200
	v_lshl_add_u64 v[154:155], v[104:105], 0, s[0:1]
	v_add_u32_e32 v104, s6, v176
	v_ashrrev_i32_e32 v105, 31, v104
	v_lshlrev_b64 v[104:105], 11, v[104:105]
	v_or_b32_e32 v84, s15, v171
	v_lshlrev_b32_e32 v142, 1, v107
	v_mov_b32_e32 v143, v1
	v_or_b32_e32 v104, v104, v103
	v_lshl_add_u64 v[82:83], v[82:83], 0, v[142:143]
	v_lshlrev_b32_e32 v84, 11, v84
	v_mov_b32_e32 v85, v1
	v_lshl_add_u64 v[156:157], v[104:105], 0, s[0:1]
	v_add_u32_e32 v104, s6, v175
	v_lshl_add_u64 v[82:83], v[82:83], 0, v[84:85]
	v_ashrrev_i32_e32 v105, 31, v104
	v_add_co_u32_e32 v84, vcc, s97, v82
	v_lshlrev_b64 v[104:105], 11, v[104:105]
	s_waitcnt vmcnt(0)
	ds_write_b128 v167, v[90:93] offset:8448
	ds_write_b128 v168, v[98:101]
	global_load_dwordx4 v[98:101], v[82:83], off offset:512
	v_addc_co_u32_e32 v85, vcc, 0, v83, vcc
	v_or_b32_e32 v104, v104, v103
	global_load_dwordx4 v[90:93], v[84:85], off offset:512
	v_add_co_u32_e32 v84, vcc, s4, v82
	v_or_b32_e32 v0, s6, v171
	v_lshl_add_u64 v[158:159], v[104:105], 0, s[0:1]
	v_add_u32_e32 v104, s6, v172
	v_addc_co_u32_e32 v85, vcc, 0, v83, vcc
	s_lshl_b64 s[44:45], s[42:43], 12
	v_lshl_or_b32 v0, v0, 11, v197
	v_ashrrev_i32_e32 v105, 31, v104
	v_add_co_u32_e32 v82, vcc, s96, v82
	v_lshl_add_u64 v[146:147], s[90:91], 0, v[0:1]
	v_lshlrev_b64 v[104:105], 11, v[104:105]
	v_or_b32_e32 v96, s44, v96
	v_mov_b32_e32 v97, s45
	v_lshlrev_b32_e32 v0, 12, v171
	global_load_dwordx4 v[86:89], v[84:85], off offset:512
	v_addc_co_u32_e32 v83, vcc, 0, v83, vcc
	v_add_u32_e32 v107, 0, v102
	v_add_u32_e32 v109, 0, v108
	v_or_b32_e32 v104, v104, v103
	v_lshl_add_u64 v[94:95], v[96:97], 0, v[94:95]
	v_lshl_or_b32 v0, s2, 21, v0
	s_mov_b32 s10, 0
	global_load_dwordx4 v[82:85], v[82:83], off offset:512
	v_add_u32_e32 v169, 0xa500, v170
	v_lshl_add_u64 v[160:161], v[104:105], 0, s[0:1]
	v_lshl_add_u64 v[162:163], v[94:95], 0, v[0:1]
	v_lshl_add_u32 v141, v172, 2, s6
	s_mov_b64 s[0:1], 0
	v_add_u32_e32 v0, v107, v108
	v_add_u32_e32 v173, v109, v102
	s_waitcnt vmcnt(0)
